# v18 + nt on P1 PROJ/AUX epilogue stores (keeps H operand resident in Infinity Cache)
# speedup vs baseline: 1.0284x; 1.0163x over previous
; DI unsigned cvtpk(float lo, float hi) { f32x2_t v = {lo, hi}; bf16x2_t b = __builtin_convertvector(v, bf16x2_t); return __builtin_bit_cast(unsigned, b); }
;     __device__ __forceinline__ void operator()(const f32x4 (&acc)[2][2][4][2], const pg8::Unit& u, int wr, int wc, int fr, int fq) const {
;         const int row0 = u.pm * 256 + wr * 64 + fr, col0 = u.pn * 256 + wc * 32 + 8 * fq;
; #pragma unroll
;         for (int ai = 0; ai < 2; ++ai)
; #pragma unroll
;             for (int m = 0; m < 4; ++m) { bf16* rowp = O + (size_t)(row0 + ai * 128 + m * 16) * NP + col0;
; #pragma unroll
;                 for (int bj = 0; bj < 2; ++bj) { const f32x4 v0 = acc[ai][bj][m][0], v1 = acc[ai][bj][m][1];
;                     u32x4 w; w.x = cvtpk(v0[0], v0[1]); w.y = cvtpk(v0[2], v0[3]); w.z = cvtpk(v1[0], v1[1]); w.w = cvtpk(v1[2], v1[3]);
;                     *(u32x4*)(rowp + bj * 128) = w; } }
;         if (u.pn == 15 && wc == 0) {
; #pragma unroll
;             for (int ai = 0; ai < 2; ++ai)
; #pragma unroll
;                 for (int m = 0; m < 4; ++m) { float* ap = aux + (size_t)(row0 + ai * 128 + m * 16) * 32 + 8 * fq;
;                     *(f32x4*)ap = acc[ai][1][m][0]; *(f32x4*)(ap + 4) = acc[ai][1][m][1]; }
;         }
;     }
.LBB0_222:
	v_lshl_add_u32 v142, s37, 8, v144
	v_lshl_or_b32 v158, s36, 8, v146
	v_ashrrev_i32_e32 v143, 31, v142
	v_ashrrev_i32_e32 v159, 31, v158
	v_lshlrev_b64 v[160:161], 13, v[142:143]
	v_lshl_add_u64 v[160:161], s[86:87], 0, v[160:161]
	v_lshlrev_b64 v[158:159], 1, v[158:159]
	v_lshl_add_u64 v[160:161], v[160:161], 0, v[158:159]
	v_cvt_pk_bf16_f32 v126, v126, v127
	v_cvt_pk_bf16_f32 v127, v128, v129
	v_cvt_pk_bf16_f32 v128, v122, v123
	v_cvt_pk_bf16_f32 v129, v124, v125
	v_cvt_pk_bf16_f32 v122, v74, v75
	v_cvt_pk_bf16_f32 v123, v76, v77
	v_cvt_pk_bf16_f32 v124, v66, v67
	v_cvt_pk_bf16_f32 v125, v68, v69
	global_store_dwordx4 v[160:161], v[122:125], off offset:256 nt
	v_cvt_pk_bf16_f32 v118, v118, v119
	v_cvt_pk_bf16_f32 v119, v120, v121
	v_or_b32_e32 v122, 16, v142
	v_ashrrev_i32_e32 v123, 31, v122
	v_lshlrev_b64 v[124:125], 13, v[122:123]
	v_lshl_add_u64 v[124:125], s[86:87], 0, v[124:125]
	v_lshl_add_u64 v[124:125], v[124:125], 0, v[158:159]
	v_cvt_pk_bf16_f32 v120, v114, v115
	v_cvt_pk_bf16_f32 v121, v116, v117
	v_cvt_pk_bf16_f32 v114, v62, v63
	v_cvt_pk_bf16_f32 v115, v64, v65
	v_cvt_pk_bf16_f32 v116, v58, v59
	v_cvt_pk_bf16_f32 v117, v60, v61
	global_store_dwordx4 v[124:125], v[114:117], off offset:256 nt
	v_cvt_pk_bf16_f32 v110, v110, v111
	v_cvt_pk_bf16_f32 v111, v112, v113
	v_or_b32_e32 v114, 32, v142
	v_ashrrev_i32_e32 v115, 31, v114
	v_lshlrev_b64 v[116:117], 13, v[114:115]
	v_lshl_add_u64 v[116:117], s[86:87], 0, v[116:117]
	v_lshl_add_u64 v[116:117], v[116:117], 0, v[158:159]
	v_cvt_pk_bf16_f32 v112, v106, v107
	v_cvt_pk_bf16_f32 v113, v108, v109
	v_cvt_pk_bf16_f32 v106, v54, v55
	v_cvt_pk_bf16_f32 v107, v56, v57
	v_cvt_pk_bf16_f32 v108, v50, v51
	v_cvt_pk_bf16_f32 v109, v52, v53
	global_store_dwordx4 v[116:117], v[106:109], off offset:256 nt
	v_cvt_pk_bf16_f32 v102, v102, v103
	v_cvt_pk_bf16_f32 v103, v104, v105
	v_or_b32_e32 v106, 48, v142
	v_ashrrev_i32_e32 v107, 31, v106
	v_lshlrev_b64 v[108:109], 13, v[106:107]
	v_lshl_add_u64 v[108:109], s[86:87], 0, v[108:109]
	v_lshl_add_u64 v[108:109], v[108:109], 0, v[158:159]
	v_cvt_pk_bf16_f32 v104, v98, v99
	v_cvt_pk_bf16_f32 v105, v100, v101
	v_cvt_pk_bf16_f32 v98, v38, v39
	v_cvt_pk_bf16_f32 v99, v40, v41
	v_cvt_pk_bf16_f32 v100, v34, v35
	v_cvt_pk_bf16_f32 v101, v36, v37
	global_store_dwordx4 v[108:109], v[98:101], off offset:256 nt
	v_cvt_pk_bf16_f32 v94, v94, v95
	v_cvt_pk_bf16_f32 v95, v96, v97
	v_add_u32_e32 v98, 0x80, v142
	v_ashrrev_i32_e32 v99, 31, v98
	v_lshlrev_b64 v[100:101], 13, v[98:99]
	v_lshl_add_u64 v[100:101], s[86:87], 0, v[100:101]
	v_lshl_add_u64 v[100:101], v[100:101], 0, v[158:159]
	v_cvt_pk_bf16_f32 v96, v90, v91
	v_cvt_pk_bf16_f32 v97, v92, v93
	v_cvt_pk_bf16_f32 v90, v30, v31
	v_cvt_pk_bf16_f32 v91, v32, v33
	v_cvt_pk_bf16_f32 v92, v26, v27
	v_cvt_pk_bf16_f32 v93, v28, v29
	global_store_dwordx4 v[100:101], v[90:93], off offset:256 nt
	v_cvt_pk_bf16_f32 v86, v86, v87
	v_cvt_pk_bf16_f32 v87, v88, v89
	v_add_u32_e32 v90, 0x90, v142
	v_ashrrev_i32_e32 v91, 31, v90
	v_lshlrev_b64 v[92:93], 13, v[90:91]
	v_lshl_add_u64 v[92:93], s[86:87], 0, v[92:93]
	v_lshl_add_u64 v[92:93], v[92:93], 0, v[158:159]
	v_cvt_pk_bf16_f32 v88, v82, v83
	v_cvt_pk_bf16_f32 v89, v84, v85
	v_cvt_pk_bf16_f32 v82, v22, v23
	v_cvt_pk_bf16_f32 v83, v24, v25
	v_cvt_pk_bf16_f32 v84, v18, v19
	v_cvt_pk_bf16_f32 v85, v20, v21
	global_store_dwordx4 v[92:93], v[82:85], off offset:256 nt
	v_cvt_pk_bf16_f32 v78, v78, v79
	v_cvt_pk_bf16_f32 v79, v80, v81
	v_add_u32_e32 v82, 0xa0, v142
	v_ashrrev_i32_e32 v83, 31, v82
	v_lshlrev_b64 v[84:85], 13, v[82:83]
	v_lshl_add_u64 v[84:85], s[86:87], 0, v[84:85]
	v_lshl_add_u64 v[84:85], v[84:85], 0, v[158:159]
	v_cvt_pk_bf16_f32 v80, v70, v71
	v_cvt_pk_bf16_f32 v81, v72, v73
	v_cvt_pk_bf16_f32 v70, v14, v15
	v_cvt_pk_bf16_f32 v71, v16, v17
	v_cvt_pk_bf16_f32 v72, v10, v11
	v_cvt_pk_bf16_f32 v73, v12, v13
	global_store_dwordx4 v[84:85], v[70:73], off offset:256 nt
	s_cmp_lg_u32 s36, 15
	s_cselect_b64 s[20:21], -1, 0
	v_add_u32_e32 v70, 0xb0, v142
	v_ashrrev_i32_e32 v71, 31, v70
	v_lshlrev_b64 v[72:73], 13, v[70:71]
	v_lshl_add_u64 v[72:73], s[86:87], 0, v[72:73]
	s_or_b64 s[20:21], s[6:7], s[20:21]
	v_lshl_add_u64 v[72:73], v[72:73], 0, v[158:159]
	v_cvt_pk_bf16_f32 v46, v46, v47
	v_cvt_pk_bf16_f32 v47, v48, v49
	v_cvt_pk_bf16_f32 v48, v42, v43
	v_cvt_pk_bf16_f32 v49, v44, v45
	v_cvt_pk_bf16_f32 v42, v6, v7
	v_cvt_pk_bf16_f32 v43, v8, v9
	v_cvt_pk_bf16_f32 v44, v2, v3
	v_cvt_pk_bf16_f32 v45, v4, v5
	s_and_b64 vcc, exec, s[20:21]
	global_store_dwordx4 v[160:161], v[126:129], off nt
	global_store_dwordx4 v[124:125], v[118:121], off nt
	global_store_dwordx4 v[116:117], v[110:113], off nt
	global_store_dwordx4 v[108:109], v[102:105], off nt
	global_store_dwordx4 v[100:101], v[94:97], off nt
	global_store_dwordx4 v[92:93], v[86:89], off nt
	global_store_dwordx4 v[84:85], v[78:81], off nt
	global_store_dwordx4 v[72:73], v[46:49], off nt
	global_store_dwordx4 v[72:73], v[42:45], off offset:256 nt
	s_cbranch_vccnz .LBB0_224
	s_nop 0
	v_lshlrev_b64 v[42:43], 7, v[142:143]
	v_lshl_add_u64 v[42:43], v[136:137], 0, v[42:43]
	global_store_dwordx4 v[42:43], v[74:77], off nt
	global_store_dwordx4 v[42:43], v[66:69], off offset:16 nt
	v_lshlrev_b64 v[42:43], 7, v[122:123]
	v_lshl_add_u64 v[42:43], v[136:137], 0, v[42:43]
	global_store_dwordx4 v[42:43], v[62:65], off nt
	global_store_dwordx4 v[42:43], v[58:61], off offset:16 nt
	v_lshlrev_b64 v[42:43], 7, v[114:115]
	v_lshl_add_u64 v[42:43], v[136:137], 0, v[42:43]
	global_store_dwordx4 v[42:43], v[54:57], off nt
	global_store_dwordx4 v[42:43], v[50:53], off offset:16 nt
	v_lshlrev_b64 v[42:43], 7, v[106:107]
	v_lshl_add_u64 v[42:43], v[136:137], 0, v[42:43]
	global_store_dwordx4 v[42:43], v[38:41], off nt
	global_store_dwordx4 v[42:43], v[34:37], off offset:16 nt
	s_nop 1
	v_lshlrev_b64 v[34:35], 7, v[98:99]
	v_lshl_add_u64 v[34:35], v[136:137], 0, v[34:35]
	global_store_dwordx4 v[34:35], v[30:33], off nt
	global_store_dwordx4 v[34:35], v[26:29], off offset:16 nt
	s_nop 1
	v_lshlrev_b64 v[26:27], 7, v[90:91]
	v_lshl_add_u64 v[26:27], v[136:137], 0, v[26:27]
	global_store_dwordx4 v[26:27], v[22:25], off nt
	global_store_dwordx4 v[26:27], v[18:21], off offset:16 nt
	s_nop 1
	v_lshlrev_b64 v[18:19], 7, v[82:83]
	v_lshl_add_u64 v[18:19], v[136:137], 0, v[18:19]
	global_store_dwordx4 v[18:19], v[14:17], off nt
	global_store_dwordx4 v[18:19], v[10:13], off offset:16 nt
	s_nop 1
	v_lshlrev_b64 v[10:11], 7, v[70:71]
	v_lshl_add_u64 v[10:11], v[136:137], 0, v[10:11]
	global_store_dwordx4 v[10:11], v[6:9], off nt
	global_store_dwordx4 v[10:11], v[2:5], off offset:16 nt
